# gemm_out xn2 stores coalesced (lane transpose) on top of mlstm decay-weight overlap
# baseline (speedup 1.0000x reference)
; DI f32x4 mfma16(bf16x8 a, bf16x8 b, f32x4 c) { return __builtin_amdgcn_mfma_f32_16x16x32_bf16(a, b, c, 0, 0, 0); }
; __device__ void mlstm_chain(const Params& p, int layer, int idx, char* smem) {
;     ...
;       for (int st = 0; st < 4; ++st) {
;         f32x4 sacc = (f32x4){0.f, 0.f, 0.f, 0.f};
;         if (st <= tb) {
; #pragma unroll
;           for (int kk = 0; kk < 2; ++kk) sacc = mfma16(ld_frag16(Ksm + (st * 16 + c) * 72 + 32 * kk + 8 * g), qf[kk], sacc);
; #pragma unroll
;           for (int rg = 0; rg < 4; ++rg) {
;             const int s = st * 16 + 4 * g + rg;
;             const float dv = (s <= t) ? __expf(us[s] - Mt) : 0.f;
;             sacc[rg] *= dv;
;             psum += sacc[rg];
;           }
;         }
;         pp[st][0] = pk_bf16(sacc[0], sacc[1]);
;         pp[st][1] = pk_bf16(sacc[2], sacc[3]);
;       }
.LBB0_553:
	s_lshl_b32 s17, s74, 6
	s_add_i32 s17, s17, s16
	v_add_u32_e32 v10, s17, v60
	v_mad_i64_i32 v[14:15], s[16:17], v10, s79, v[38:39]
	global_load_dwordx4 v[18:21], v[14:15], off offset:2560
	global_load_dwordx4 v[10:13], v[14:15], off offset:3072
	s_nop 0
	global_load_dwordx4 v[14:17], v[14:15], off offset:3584
	v_add_u32_e32 v53, s29, v65
	ds_read_b32 v22, v53 offset:18432
	v_add3_u32 v70, s73, v56, v49
	v_add_u32_e32 v30, s72, v49
	v_cndmask_b32_e64 v31, 0, 1, s[8:9]
	v_cmp_ne_u32_e64 s[72:73], 1, v31
	s_waitcnt lgkmcnt(0)
	v_max_f32_e32 v22, v22, v22
	v_max_f32_e32 v41, v0, v22
	ds_read_b128 v[26:29], v70
	ds_read_b128 v[22:25], v70 offset:64
	v_mov_b32_e32 v0, 0
	s_andn2_b64 vcc, exec, s[8:9]
	v_add_u32_e32 v75, v30, v59
	v_mov_b32_e32 v73, 0
	v_mov_b32_e32 v72, 0
	v_mov_b32_e32 v71, 0
	v_mov_b32_e32 v74, 0
	s_cbranch_vccnz .LBB0_563
	v_add_u32_e32 v204, s29, v66
	ds_read_b32 v200, v204 offset:54272
	ds_read_b32 v201, v204 offset:54276
	ds_read_b32 v202, v204 offset:54280
	ds_read_b32 v203, v204 offset:54284
	ds_read_b128 v[30:33], v75
	ds_read_b128 v[76:79], v75 offset:64
	s_waitcnt lgkmcnt(2)
	v_sub_f32_e32 v200, v200, v41
	v_sub_f32_e32 v201, v201, v41
	v_sub_f32_e32 v202, v202, v41
	v_sub_f32_e32 v203, v203, v41
	v_mul_f32_e32 v200, 0x3fb8aa3b, v200
	v_mul_f32_e32 v201, 0x3fb8aa3b, v201
	v_mul_f32_e32 v202, 0x3fb8aa3b, v202
	v_mul_f32_e32 v203, 0x3fb8aa3b, v203
	v_exp_f32_e32 v200, v200
	v_exp_f32_e32 v201, v201
	v_exp_f32_e32 v202, v202
	v_exp_f32_e32 v203, v203
	s_waitcnt lgkmcnt(1)
	v_mfma_f32_16x16x32_bf16 v[30:33], v[30:33], v[26:29], 0
	s_waitcnt lgkmcnt(0)
	v_mfma_f32_16x16x32_bf16 v[30:33], v[76:79], v[22:25], v[30:33]
	v_cndmask_b32_e64 v72, 0, v200, s[70:71]
	v_cndmask_b32_e64 v73, 0, v201, s[68:69]
	v_cndmask_b32_e64 v0, 0, v202, s[66:67]
	v_cndmask_b32_e64 v76, 0, v203, s[64:65]
	s_nop 4
	v_fma_f32 v74, v30, v72, 0
	v_fmac_f32_e32 v74, v31, v73
	v_fmac_f32_e32 v74, v32, v0
	v_mul_f32_e32 v71, v30, v72
	v_mul_f32_e32 v72, v31, v73
	v_mul_f32_e32 v73, v32, v0
	v_mul_f32_e32 v0, v33, v76
	v_fmac_f32_e32 v74, v33, v76
.LBB0_563:
	v_cndmask_b32_e64 v30, 0, 1, s[10:11]
	v_cmp_ne_u32_e64 s[74:75], 1, v30
	s_andn2_b64 vcc, exec, s[10:11]
	v_mov_b32_e32 v77, 0
	s_cbranch_vccnz .LBB0_568
	v_add_u32_e32 v204, s29, v66
	ds_read_b32 v200, v204 offset:54336
	ds_read_b32 v201, v204 offset:54340
	ds_read_b32 v202, v204 offset:54344
	ds_read_b32 v203, v204 offset:54348
	ds_read_b128 v[30:33], v75 offset:2304
	ds_read_b128 v[76:79], v75 offset:2368
	s_waitcnt lgkmcnt(2)
	v_sub_f32_e32 v200, v200, v41
	v_sub_f32_e32 v201, v201, v41
	v_sub_f32_e32 v202, v202, v41
	v_sub_f32_e32 v203, v203, v41
	v_mul_f32_e32 v200, 0x3fb8aa3b, v200
	v_mul_f32_e32 v201, 0x3fb8aa3b, v201
	v_mul_f32_e32 v202, 0x3fb8aa3b, v202
	v_mul_f32_e32 v203, 0x3fb8aa3b, v203
	v_exp_f32_e32 v200, v200
	v_exp_f32_e32 v201, v201
	v_exp_f32_e32 v202, v202
	v_exp_f32_e32 v203, v203
	s_waitcnt lgkmcnt(1)
	v_mfma_f32_16x16x32_bf16 v[30:33], v[30:33], v[26:29], 0
	s_waitcnt lgkmcnt(0)
	v_mfma_f32_16x16x32_bf16 v[30:33], v[76:79], v[22:25], v[30:33]
	v_cndmask_b32_e64 v78, 0, v200, s[62:63]
	v_cndmask_b32_e64 v79, 0, v201, s[60:61]
	v_cndmask_b32_e64 v77, 0, v202, s[58:59]
	v_cndmask_b32_e64 v80, 0, v203, s[56:57]
	s_nop 4
	v_fmac_f32_e32 v74, v30, v78
	v_fmac_f32_e32 v74, v31, v79
	v_fmac_f32_e32 v74, v32, v77
	v_mul_f32_e32 v76, v30, v78
	v_mul_f32_e32 v78, v31, v79
	v_mul_f32_e32 v79, v32, v77
	v_mul_f32_e32 v77, v33, v80
	v_fmac_f32_e32 v74, v33, v80
.LBB0_574:
	v_cndmask_b32_e64 v30, 0, 1, s[12:13]
	v_cmp_ne_u32_e64 s[76:77], 1, v30
	s_andn2_b64 vcc, exec, s[12:13]
	v_mov_b32_e32 v81, 0
	s_cbranch_vccnz .LBB0_579
	v_add_u32_e32 v204, s29, v66
	ds_read_b32 v200, v204 offset:54400
	ds_read_b32 v201, v204 offset:54404
	ds_read_b32 v202, v204 offset:54408
	ds_read_b32 v203, v204 offset:54412
	ds_read_b128 v[30:33], v75 offset:4608
	ds_read_b128 v[80:83], v75 offset:4672
	s_waitcnt lgkmcnt(2)
	v_sub_f32_e32 v200, v200, v41
	v_sub_f32_e32 v201, v201, v41
	v_sub_f32_e32 v202, v202, v41
	v_sub_f32_e32 v203, v203, v41
	v_mul_f32_e32 v200, 0x3fb8aa3b, v200
	v_mul_f32_e32 v201, 0x3fb8aa3b, v201
	v_mul_f32_e32 v202, 0x3fb8aa3b, v202
	v_mul_f32_e32 v203, 0x3fb8aa3b, v203
	v_exp_f32_e32 v200, v200
	v_exp_f32_e32 v201, v201
	v_exp_f32_e32 v202, v202
	v_exp_f32_e32 v203, v203
	s_waitcnt lgkmcnt(1)
	v_mfma_f32_16x16x32_bf16 v[30:33], v[30:33], v[26:29], 0
	s_waitcnt lgkmcnt(0)
	v_mfma_f32_16x16x32_bf16 v[30:33], v[80:83], v[22:25], v[30:33]
	v_cndmask_b32_e64 v82, 0, v200, s[54:55]
	v_cndmask_b32_e64 v83, 0, v201, s[52:53]
	v_cndmask_b32_e64 v81, 0, v202, s[50:51]
	v_cndmask_b32_e64 v84, 0, v203, s[48:49]
	s_nop 4
	v_fmac_f32_e32 v74, v30, v82
	v_fmac_f32_e32 v74, v31, v83
	v_fmac_f32_e32 v74, v32, v81
	v_mul_f32_e32 v80, v30, v82
	v_mul_f32_e32 v82, v31, v83
	v_mul_f32_e32 v83, v32, v81
	v_mul_f32_e32 v81, v33, v84
	v_fmac_f32_e32 v74, v33, v84
	s_mov_b64 s[16:17], -1
	s_and_b64 vcc, exec, s[6:7]
	s_cbranch_vccz .LBB0_594
.LBB0_585:
	v_add_u32_e32 v204, s29, v66
	ds_read_b32 v200, v204 offset:54464
	ds_read_b32 v201, v204 offset:54468
	ds_read_b32 v202, v204 offset:54472
	ds_read_b32 v203, v204 offset:54476
	ds_read_b128 v[30:33], v75 offset:6912
	ds_read_b128 v[84:87], v75 offset:6976
	s_waitcnt lgkmcnt(2)
	v_sub_f32_e32 v200, v200, v41
	v_sub_f32_e32 v201, v201, v41
	v_sub_f32_e32 v202, v202, v41
	v_sub_f32_e32 v203, v203, v41
	v_mul_f32_e32 v200, 0x3fb8aa3b, v200
	v_mul_f32_e32 v201, 0x3fb8aa3b, v201
	v_mul_f32_e32 v202, 0x3fb8aa3b, v202
	v_mul_f32_e32 v203, 0x3fb8aa3b, v203
	v_exp_f32_e32 v200, v200
	v_exp_f32_e32 v201, v201
	v_exp_f32_e32 v202, v202
	v_exp_f32_e32 v203, v203
	s_waitcnt lgkmcnt(1)
	v_mfma_f32_16x16x32_bf16 v[30:33], v[30:33], v[26:29], 0
	s_waitcnt lgkmcnt(0)
	v_mfma_f32_16x16x32_bf16 v[30:33], v[84:87], v[22:25], v[30:33]
	v_cndmask_b32_e64 v85, 0, v200, s[46:47]
	v_cndmask_b32_e64 v86, 0, v201, s[44:45]
	v_cndmask_b32_e64 v75, 0, v202, s[42:43]
	v_cndmask_b32_e64 v87, 0, v203, s[40:41]
	s_nop 4
	v_mul_f32_e32 v84, v30, v85
	v_fma_f32 v30, v30, v85, v74
	v_fmac_f32_e32 v30, v31, v86
	v_fmac_f32_e32 v30, v32, v75
	v_mul_f32_e32 v85, v31, v86
	v_mul_f32_e32 v31, v32, v75
	v_mul_f32_e32 v32, v33, v87
	v_fmac_f32_e32 v30, v33, v87
	s_mov_b64 s[16:17], 0

; template <int EPI>
; DI void gemm_epilogue(const Params& p, int layer, f32x4 (&acc)[2][2][4][2], int brow, int bcol, int pn, int wr, int wc,
;                       int fr, int fq, char* smem, int ksplit = -1) {
;     ...
;     f32x4 gv[2][2], gs[2][2];
; #pragma unroll
;     for (int bj = 0; bj < 2; ++bj)
; #pragma unroll
;       for (int n = 0; n < 2; ++n) {
;         const int col = colb + bj * 128 + n * 4;
;         gv[bj][n] = *(const f32x4*)(gate + col);
;         if (EPI == EPI_OUT) gs[bj][n] = *(const f32x4*)(g2 + col) * (*(const f32x4*)(sc2 + col) + 1.f);
;       }
; #pragma unroll
;     for (int am = 0; am < 4; ++am) {
;       const int ai = am >> 1, m0 = (am & 1) * 2;
;       __builtin_amdgcn_sched_barrier(0);
;       f32x4 xv[2][2][2];
; #pragma unroll
;       for (int mm = 0; mm < 2; ++mm)
; #pragma unroll
;         for (int bj = 0; bj < 2; ++bj)
; #pragma unroll
;           for (int n = 0; n < 2; ++n)
;             xv[mm][bj][n] = *(const f32x4*)(src + (size_t)(ai * 128 + wr * 64 + (m0 + mm) * 16 + fr) * DM + colb + bj * 128 + n * 4);
;       __builtin_amdgcn_sched_barrier(0);
; #pragma unroll
;       for (int mm = 0; mm < 2; ++mm) {
;         const int m = m0 + mm;
;         const int rl = ai * 128 + wr * 64 + m * 16 + fr;
;         float ssq = 0.f;
; #pragma unroll
;         for (int bj = 0; bj < 2; ++bj) {
;           u32x4 ob;
; #pragma unroll
;           for (int n = 0; n < 2; ++n) {
;             const int col = colb + bj * 128 + n * 4;
;             f32x4 o = xv[mm][bj][n] + gv[bj][n] * acc[ai][bj][m][n];
;             *(f32x4*)(dst + (size_t)rl * DM + col) = o;
.LBB0_913:
	v_and_b32_e32 v231, 63, v234
	v_lshrrev_b32_e32 v232, 2, v231
	v_and_b32_e32 v233, 15, v231
	v_sub_u32_e32 v233, v232, v233
	v_lshlrev_b32_e32 v233, 11, v233
	v_and_b32_e32 v229, 3, v231
	v_lshl_or_b32 v230, v229, 4, v232
	v_lshlrev_b32_e32 v230, 2, v230
	v_lshrrev_b32_e32 v232, 4, v231
	v_sub_u32_e32 v232, v229, v232
	v_lshl_add_u32 v228, v232, 4, v233
	v_ashrrev_i32_e32 v229, 31, v228
	s_lshl_b32 s9, s16, 8
	s_min_i32 s16, s14, 0x8000
	s_ashr_i32 s16, s16, 11
	s_add_i32 s16, s16, s36
	s_mul_i32 s16, s16, 6
	s_ashr_i32 s17, s16, 31
	v_readlane_b32 s60, v254, 45
	s_lshl_b64 s[16:17], s[16:17], 12
	v_readlane_b32 s64, v254, 49
	v_readlane_b32 s65, v254, 50
	s_add_u32 s22, s64, s16
	v_bfe_u32 v147, v146, 4, 2
	s_addc_u32 s23, s65, s17
	s_add_u32 s16, s22, 0x2000
	v_lshl_or_b32 v106, v147, 3, s9
	s_addc_u32 s17, s23, 0
	v_or_b32_e32 v178, s39, v106
	s_add_u32 s22, s22, 0x4000
	v_ashrrev_i32_e32 v179, 31, v178
	s_addc_u32 s23, s23, 0
	v_lshlrev_b64 v[200:201], 2, v[178:179]
	v_lshl_add_u64 v[114:115], s[16:17], 0, v[200:201]
	v_lshl_add_u64 v[156:157], s[6:7], 0, v[200:201]
	v_lshl_add_u64 v[152:153], s[22:23], 0, v[200:201]
	global_load_dwordx4 v[106:109], v[114:115], off offset:16
	s_nop 0
	global_load_dwordx4 v[114:117], v[114:115], off
	s_nop 0
	global_load_dwordx4 v[118:121], v[156:157], off offset:16
	global_load_dwordx4 v[130:133], v[156:157], off
	global_load_dwordx4 v[148:151], v[152:153], off offset:16
	s_nop 0
	global_load_dwordx4 v[152:155], v[152:153], off
	v_and_or_b32 v192, v146, 15, s33
	v_lshl_add_u64 v[198:199], s[20:21], 0, v[200:201]
	v_cmp_eq_u32_e32 vcc, 0, v147
	v_readlane_b32 s61, v254, 46
	v_readlane_b32 s62, v254, 47
	v_readlane_b32 s63, v254, 48
	v_readlane_b32 s66, v254, 51
	v_readlane_b32 s67, v254, 52
	v_readlane_b32 s68, v254, 53
	v_readlane_b32 s69, v254, 54
	v_readlane_b32 s70, v254, 55
	v_readlane_b32 s71, v254, 56
	v_readlane_b32 s72, v254, 57
	v_readlane_b32 s73, v254, 58
	v_readlane_b32 s74, v254, 59
	v_readlane_b32 s75, v254, 60
	s_waitcnt vmcnt(0)
	v_pk_add_f32 v[154:155], v[154:155], 1.0 op_sel_hi:[1,0]
	s_nop 0
	v_pk_mul_f32 v[184:185], v[132:133], v[154:155]
	v_pk_add_f32 v[132:133], v[148:149], 1.0 op_sel_hi:[1,0]
	v_pk_add_f32 v[152:153], v[152:153], 1.0 op_sel_hi:[1,0]
	v_pk_mul_f32 v[182:183], v[118:119], v[132:133]
	v_or_b32_e32 v118, 0x80, v178
	v_ashrrev_i32_e32 v119, 31, v118
	v_pk_mul_f32 v[186:187], v[130:131], v[152:153]
	v_lshlrev_b64 v[152:153], 2, v[118:119]
	v_pk_add_f32 v[130:131], v[150:151], 1.0 op_sel_hi:[1,0]
	v_lshl_add_u64 v[118:119], s[16:17], 0, v[152:153]
	v_pk_mul_f32 v[180:181], v[120:121], v[130:131]
	global_load_dwordx4 v[118:121], v[118:119], off
	s_nop 0
	global_load_dwordx4 v[148:151], v[156:157], off offset:528
	global_load_dwordx4 v[130:133], v[156:157], off offset:512
	v_lshl_add_u64 v[156:157], s[22:23], 0, v[152:153]
	global_load_dwordx4 v[152:155], v[156:157], off offset:16
	s_nop 0
	global_load_dwordx4 v[156:159], v[156:157], off
	s_waitcnt vmcnt(1)
	v_pk_add_f32 v[154:155], v[154:155], 1.0 op_sel_hi:[1,0]
	s_waitcnt vmcnt(0)
	v_pk_add_f32 v[156:157], v[156:157], 1.0 op_sel_hi:[1,0]
	v_pk_add_f32 v[158:159], v[158:159], 1.0 op_sel_hi:[1,0]
	v_pk_mul_f32 v[190:191], v[130:131], v[156:157]
	v_or_b32_e32 v130, 0x84, v178
	v_ashrrev_i32_e32 v131, 31, v130
	v_lshl_add_u64 v[130:131], v[130:131], 2, s[16:17]
	v_pk_mul_f32 v[188:189], v[132:133], v[158:159]
	global_load_dwordx4 v[130:133], v[130:131], off
	v_pk_add_f32 v[152:153], v[152:153], 1.0 op_sel_hi:[1,0]
	v_pk_mul_f32 v[194:195], v[150:151], v[154:155]
	v_pk_mul_f32 v[196:197], v[148:149], v[152:153]
	v_or_b32_e32 v202, 16, v192
	v_ashrrev_i32_e32 v193, 31, v192
	v_ashrrev_i32_e32 v203, 31, v202
	v_lshlrev_b64 v[224:225], 12, v[192:193]
	v_lshlrev_b64 v[204:205], 12, v[202:203]
	v_lshl_add_u64 v[146:147], v[198:199], 0, v[224:225]
	v_lshl_add_u64 v[150:151], v[198:199], 0, v[204:205]
	global_load_dwordx4 v[208:211], v[146:147], off offset:16
	global_load_dwordx4 v[212:215], v[146:147], off
	global_load_dwordx4 v[216:219], v[146:147], off offset:528
	global_load_dwordx4 v[220:223], v[146:147], off offset:512
	global_load_dwordx4 v[154:157], v[150:151], off offset:16
	global_load_dwordx4 v[158:161], v[150:151], off
	s_nop 0
	global_load_dwordx4 v[146:149], v[150:151], off offset:528
	s_nop 0
	global_load_dwordx4 v[150:153], v[150:151], off offset:512
	s_waitcnt vmcnt(6)
	v_pk_fma_f32 v[142:143], v[142:143], v[114:115], v[212:213]
	v_lshl_add_u64 v[224:225], s[18:19], 0, v[224:225]
	v_mul_f32_e32 v203, v143, v143
	v_pk_fma_f32 v[144:145], v[144:145], v[116:117], v[214:215]
	v_fmac_f32_e32 v203, v142, v142
	v_lshl_add_u64 v[200:201], v[224:225], 0, v[200:201]
	v_fmac_f32_e32 v203, v144, v144
	global_store_dwordx4 v[200:201], v[142:145], off
	v_fmac_f32_e32 v203, v145, v145
	v_pk_fma_f32 v[138:139], v[138:139], v[106:107], v[208:209]
	v_pk_mul_f32 v[144:145], v[184:185], v[144:145]
	v_pk_mul_f32 v[142:143], v[186:187], v[142:143]
	v_pk_fma_f32 v[140:141], v[140:141], v[108:109], v[210:211]
	v_cvt_pk_bf16_f32 v142, v142, v143
	v_cvt_pk_bf16_f32 v143, v144, v145
	v_mul_f32_e32 v144, v139, v139
	v_fmac_f32_e32 v144, v138, v138
	v_add_u32_e32 v226, s14, v192
	v_fmac_f32_e32 v144, v140, v140
	v_ashrrev_i32_e32 v227, 31, v226
	global_store_dwordx4 v[200:201], v[138:141], off offset:16
	v_fmac_f32_e32 v144, v141, v141
	s_waitcnt vmcnt(6)
; DI float xsum32(float x) { auto r = __builtin_amdgcn_permlane32_swap(__float_as_uint(x), __float_as_uint(x), false, false); return __uint_as_float(r[0]) + __uint_as_float(r[1]); }
; DI float xsum16(float x) { auto r = __builtin_amdgcn_permlane16_swap(__float_as_uint(x), __float_as_uint(x), false, false); return __uint_as_float(r[0]) + __uint_as_float(r[1]); }
; template <int EPI>
; DI void gemm_epilogue(const Params& p, int layer, f32x4 (&acc)[2][2][4][2], int brow, int bcol, int pn, int wr, int wc,
;                       int fr, int fq, char* smem, int ksplit = -1) {
;     ...
;         for (int bj = 0; bj < 2; ++bj) {
;           u32x4 ob;
; #pragma unroll
;           for (int n = 0; n < 2; ++n) {
;             const int col = colb + bj * 128 + n * 4;
;             f32x4 o = xv[mm][bj][n] + gv[bj][n] * acc[ai][bj][m][n];
;             *(f32x4*)(dst + (size_t)rl * DM + col) = o;
;             if (EPI == EPI_OUT) {
;               ssq += o[0] * o[0] + o[1] * o[1] + o[2] * o[2] + o[3] * o[3];
;               o = o * gs[bj][n];
;               ob[2 * n] = pk_bf16(o[0], o[1]);
;               ob[2 * n + 1] = pk_bf16(o[2], o[3]);
;             }
;           }
;           if (EPI == EPI_OUT) *(u32x4*)(p.xn2 + (size_t)(brow + rl) * DM + colb + bj * 128) = ob;
;         }
;         if (EPI == EPI_OUT) {
;           ssq = xsum16(ssq);
;           ssq = xsum32(ssq);
;           if (fq == 0) atomicAdd(p.rowss + (size_t)layer * NTOK + brow + rl, ssq);
	v_pk_fma_f32 v[134:135], v[134:135], v[118:119], v[220:221]
	v_pk_mul_f32 v[140:141], v[180:181], v[140:141]
	v_lshlrev_b64 v[226:227], 11, v[226:227]
	v_pk_mul_f32 v[138:139], v[182:183], v[138:139]
	v_cvt_pk_bf16_f32 v145, v140, v141
	v_mul_f32_e32 v140, v135, v135
	v_add_f32_e32 v203, v203, v144
	v_cvt_pk_bf16_f32 v144, v138, v139
	v_lshl_add_u64 v[138:139], s[76:77], 0, v[226:227]
	v_pk_fma_f32 v[136:137], v[136:137], v[120:121], v[222:223]
	v_fmac_f32_e32 v140, v134, v134
	v_lshl_add_u64 v[138:139], v[178:179], 1, v[138:139]
	v_fmac_f32_e32 v140, v136, v136
	v_lshl_add_u64 v[138:139], v[138:139], 0, v[228:229]
	ds_bpermute_b32 v142, v230, v142
	ds_bpermute_b32 v143, v230, v143
	ds_bpermute_b32 v144, v230, v144
	ds_bpermute_b32 v145, v230, v145
	s_waitcnt lgkmcnt(0)
	global_store_dwordx4 v[138:139], v[142:145], off
	global_store_dwordx4 v[200:201], v[134:137], off offset:512
	v_fmac_f32_e32 v140, v137, v137
	v_pk_fma_f32 v[126:127], v[126:127], v[130:131], v[216:217]
	v_pk_mul_f32 v[136:137], v[188:189], v[136:137]
	v_pk_mul_f32 v[134:135], v[190:191], v[134:135]
	v_pk_fma_f32 v[128:129], v[128:129], v[132:133], v[218:219]
	v_cvt_pk_bf16_f32 v134, v134, v135
	v_cvt_pk_bf16_f32 v135, v136, v137
	v_mul_f32_e32 v136, v127, v127
	v_fmac_f32_e32 v136, v126, v126
	v_fmac_f32_e32 v136, v128, v128
	v_add_f32_e32 v140, v203, v140
	v_fmac_f32_e32 v136, v129, v129
	global_store_dwordx4 v[200:201], v[126:129], off offset:528
	v_add_f32_e32 v140, v140, v136
	s_nop 0
	v_pk_mul_f32 v[126:127], v[196:197], v[126:127]
	v_pk_mul_f32 v[128:129], v[194:195], v[128:129]
	v_cvt_pk_bf16_f32 v136, v126, v127
	v_mov_b32_e32 v126, v140
	s_nop 1
	v_permlane16_swap_b32_e32 v140, v126
	v_add_f32_e32 v126, v140, v126
	v_mov_b32_e32 v127, v126
	v_cvt_pk_bf16_f32 v137, v128, v129
	s_nop 0
	v_permlane32_swap_b32_e32 v126, v127
	ds_bpermute_b32 v134, v230, v134
	ds_bpermute_b32 v135, v230, v135
	ds_bpermute_b32 v136, v230, v136
	ds_bpermute_b32 v137, v230, v137
	s_waitcnt lgkmcnt(0)
	global_store_dwordx4 v[138:139], v[134:137], off offset:256
	s_and_saveexec_b64 s[16:17], vcc
	s_cbranch_execz .LBB0_915
	s_lshl_b64 s[20:21], s[14:15], 2
	s_add_u32 s20, s43, s20
	s_addc_u32 s21, s47, s21
	v_lshl_add_u64 v[128:129], v[192:193], 2, s[20:21]
	v_add_f32_e32 v126, v126, v127
	global_atomic_add_f32 v[128:129], v126, off
.LBB0_915:
	s_or_b64 exec, exec, s[16:17]
	s_waitcnt vmcnt(8)
	v_pk_fma_f32 v[122:123], v[122:123], v[114:115], v[158:159]
	v_lshl_add_u64 v[126:127], s[18:19], 0, v[204:205]
	v_mul_f32_e32 v134, v123, v123
	v_pk_fma_f32 v[124:125], v[124:125], v[116:117], v[160:161]
	v_fmac_f32_e32 v134, v122, v122
	v_lshl_add_u64 v[126:127], v[178:179], 2, v[126:127]
	v_fmac_f32_e32 v134, v124, v124
	global_store_dwordx4 v[126:127], v[122:125], off
	v_fmac_f32_e32 v134, v125, v125
	v_pk_fma_f32 v[110:111], v[110:111], v[106:107], v[154:155]
	v_pk_mul_f32 v[124:125], v[184:185], v[124:125]
	v_pk_mul_f32 v[122:123], v[186:187], v[122:123]
	v_pk_fma_f32 v[112:113], v[112:113], v[108:109], v[156:157]
	v_cvt_pk_bf16_f32 v122, v122, v123
	v_cvt_pk_bf16_f32 v123, v124, v125
	v_mul_f32_e32 v124, v111, v111
	v_fmac_f32_e32 v124, v110, v110
	v_add_u32_e32 v128, s14, v202
	v_fmac_f32_e32 v124, v112, v112
	v_ashrrev_i32_e32 v129, 31, v128
	global_store_dwordx4 v[126:127], v[110:113], off offset:16
	v_fmac_f32_e32 v124, v113, v113
	s_waitcnt vmcnt(8)
	v_pk_fma_f32 v[102:103], v[102:103], v[118:119], v[150:151]
	v_pk_mul_f32 v[112:113], v[180:181], v[112:113]
	v_lshlrev_b64 v[128:129], 11, v[128:129]
	v_pk_mul_f32 v[110:111], v[182:183], v[110:111]
	v_cvt_pk_bf16_f32 v125, v112, v113
	v_mul_f32_e32 v112, v103, v103
	v_add_f32_e32 v134, v134, v124
	v_cvt_pk_bf16_f32 v124, v110, v111
	v_lshl_add_u64 v[110:111], s[76:77], 0, v[128:129]
	v_pk_fma_f32 v[104:105], v[104:105], v[120:121], v[152:153]
	v_fmac_f32_e32 v112, v102, v102
	v_lshl_add_u64 v[110:111], v[178:179], 1, v[110:111]
	v_fmac_f32_e32 v112, v104, v104
	v_lshl_add_u64 v[110:111], v[110:111], 0, v[228:229]
	ds_bpermute_b32 v122, v230, v122
	ds_bpermute_b32 v123, v230, v123
	ds_bpermute_b32 v124, v230, v124
	ds_bpermute_b32 v125, v230, v125
	s_waitcnt lgkmcnt(0)
	global_store_dwordx4 v[110:111], v[122:125], off
	global_store_dwordx4 v[126:127], v[102:105], off offset:512
	v_fmac_f32_e32 v112, v105, v105
	v_pk_fma_f32 v[98:99], v[98:99], v[130:131], v[146:147]
	v_pk_mul_f32 v[104:105], v[188:189], v[104:105]
	v_pk_mul_f32 v[102:103], v[190:191], v[102:103]
	v_pk_fma_f32 v[100:101], v[100:101], v[132:133], v[148:149]
	v_cvt_pk_bf16_f32 v102, v102, v103
	v_cvt_pk_bf16_f32 v103, v104, v105
	v_mul_f32_e32 v104, v99, v99
	v_fmac_f32_e32 v104, v98, v98
	v_fmac_f32_e32 v104, v100, v100
	v_add_f32_e32 v112, v134, v112
	v_fmac_f32_e32 v104, v101, v101
	global_store_dwordx4 v[126:127], v[98:101], off offset:528
	v_add_f32_e32 v112, v112, v104
	s_nop 0
	v_pk_mul_f32 v[98:99], v[196:197], v[98:99]
	v_pk_mul_f32 v[100:101], v[194:195], v[100:101]
	v_cvt_pk_bf16_f32 v104, v98, v99
	v_mov_b32_e32 v98, v112
	s_nop 1
	v_permlane16_swap_b32_e32 v112, v98
	v_add_f32_e32 v98, v112, v98
	v_mov_b32_e32 v99, v98
	v_cvt_pk_bf16_f32 v105, v100, v101
	s_nop 0
	v_permlane32_swap_b32_e32 v98, v99
	ds_bpermute_b32 v102, v230, v102
	ds_bpermute_b32 v103, v230, v103
	ds_bpermute_b32 v104, v230, v104
	ds_bpermute_b32 v105, v230, v105
	s_waitcnt lgkmcnt(0)
	global_store_dwordx4 v[110:111], v[102:105], off offset:256
	s_and_saveexec_b64 s[16:17], vcc
	s_cbranch_execz .LBB0_917
	s_lshl_b64 s[20:21], s[14:15], 2
	s_add_u32 s20, s43, s20
	s_addc_u32 s21, s47, s21
	v_lshl_add_u64 v[100:101], v[192:193], 2, s[20:21]
	v_add_f32_e32 v98, v98, v99
	global_atomic_add_f32 v[100:101], v98, off offset:64
; DI float xsum32(float x) { auto r = __builtin_amdgcn_permlane32_swap(__float_as_uint(x), __float_as_uint(x), false, false); return __uint_as_float(r[0]) + __uint_as_float(r[1]); }
; DI float xsum16(float x) { auto r = __builtin_amdgcn_permlane16_swap(__float_as_uint(x), __float_as_uint(x), false, false); return __uint_as_float(r[0]) + __uint_as_float(r[1]); }
; template <int EPI>
; DI void gemm_epilogue(const Params& p, int layer, f32x4 (&acc)[2][2][4][2], int brow, int bcol, int pn, int wr, int wc,
;                       int fr, int fq, char* smem, int ksplit = -1) {
;     ...
;         for (int bj = 0; bj < 2; ++bj) {
;           u32x4 ob;
; #pragma unroll
;           for (int n = 0; n < 2; ++n) {
;             const int col = colb + bj * 128 + n * 4;
;             f32x4 o = xv[mm][bj][n] + gv[bj][n] * acc[ai][bj][m][n];
;             *(f32x4*)(dst + (size_t)rl * DM + col) = o;
;             if (EPI == EPI_OUT) {
;               ssq += o[0] * o[0] + o[1] * o[1] + o[2] * o[2] + o[3] * o[3];
;               o = o * gs[bj][n];
;               ob[2 * n] = pk_bf16(o[0], o[1]);
;               ob[2 * n + 1] = pk_bf16(o[2], o[3]);
;             }
;           }
;           if (EPI == EPI_OUT) *(u32x4*)(p.xn2 + (size_t)(brow + rl) * DM + colb + bj * 128) = ob;
;         }
;         if (EPI == EPI_OUT) {
;           ssq = xsum16(ssq);
;           ssq = xsum32(ssq);
;           if (fq == 0) atomicAdd(p.rowss + (size_t)layer * NTOK + brow + rl, ssq);
.LBB0_917:
	s_or_b64 exec, exec, s[16:17]
	v_or_b32_e32 v150, 32, v192
	v_or_b32_e32 v126, 48, v192
	v_ashrrev_i32_e32 v151, 31, v150
	v_ashrrev_i32_e32 v127, 31, v126
	v_lshlrev_b64 v[152:153], 12, v[150:151]
	v_lshlrev_b64 v[128:129], 12, v[126:127]
	v_lshl_add_u64 v[98:99], v[198:199], 0, v[152:153]
	v_lshl_add_u64 v[102:103], v[198:199], 0, v[128:129]
	global_load_dwordx4 v[134:137], v[98:99], off offset:16
	global_load_dwordx4 v[138:141], v[98:99], off
	global_load_dwordx4 v[142:145], v[98:99], off offset:528
	global_load_dwordx4 v[146:149], v[98:99], off offset:512
	global_load_dwordx4 v[110:113], v[102:103], off offset:16
	global_load_dwordx4 v[122:125], v[102:103], off
	s_nop 0
	global_load_dwordx4 v[98:101], v[102:103], off offset:528
	s_nop 0
	global_load_dwordx4 v[102:105], v[102:103], off offset:512
	s_waitcnt vmcnt(6)
	v_pk_fma_f32 v[94:95], v[94:95], v[114:115], v[138:139]
	v_lshl_add_u64 v[152:153], s[18:19], 0, v[152:153]
	v_mul_f32_e32 v127, v95, v95
	v_pk_fma_f32 v[96:97], v[96:97], v[116:117], v[140:141]
	v_fmac_f32_e32 v127, v94, v94
	v_lshl_add_u64 v[138:139], v[178:179], 2, v[152:153]
	v_fmac_f32_e32 v127, v96, v96
	global_store_dwordx4 v[138:139], v[94:97], off
	v_fmac_f32_e32 v127, v97, v97
	v_pk_fma_f32 v[90:91], v[90:91], v[106:107], v[134:135]
	v_pk_mul_f32 v[96:97], v[184:185], v[96:97]
	v_pk_mul_f32 v[94:95], v[186:187], v[94:95]
	v_pk_fma_f32 v[92:93], v[92:93], v[108:109], v[136:137]
	v_cvt_pk_bf16_f32 v94, v94, v95
	v_cvt_pk_bf16_f32 v95, v96, v97
	v_mul_f32_e32 v96, v91, v91
	v_fmac_f32_e32 v96, v90, v90
	v_add_u32_e32 v150, s14, v150
	v_fmac_f32_e32 v96, v92, v92
	v_ashrrev_i32_e32 v151, 31, v150
	global_store_dwordx4 v[138:139], v[90:93], off offset:16
	v_fmac_f32_e32 v96, v93, v93
	s_waitcnt vmcnt(6)
	v_pk_fma_f32 v[86:87], v[86:87], v[118:119], v[146:147]
	v_pk_mul_f32 v[92:93], v[180:181], v[92:93]
	v_lshlrev_b64 v[150:151], 11, v[150:151]
	v_pk_mul_f32 v[90:91], v[182:183], v[90:91]
	v_cvt_pk_bf16_f32 v97, v92, v93
	v_mul_f32_e32 v92, v87, v87
	v_add_f32_e32 v127, v127, v96
	v_cvt_pk_bf16_f32 v96, v90, v91
	v_lshl_add_u64 v[90:91], s[76:77], 0, v[150:151]
	v_pk_fma_f32 v[88:89], v[88:89], v[120:121], v[148:149]
	v_fmac_f32_e32 v92, v86, v86
	v_lshl_add_u64 v[90:91], v[178:179], 1, v[90:91]
	v_fmac_f32_e32 v92, v88, v88
	v_lshl_add_u64 v[90:91], v[90:91], 0, v[228:229]
	ds_bpermute_b32 v94, v230, v94
	ds_bpermute_b32 v95, v230, v95
	ds_bpermute_b32 v96, v230, v96
	ds_bpermute_b32 v97, v230, v97
	s_waitcnt lgkmcnt(0)
	global_store_dwordx4 v[90:91], v[94:97], off
	global_store_dwordx4 v[138:139], v[86:89], off offset:512
	v_fmac_f32_e32 v92, v89, v89
	v_pk_fma_f32 v[82:83], v[82:83], v[130:131], v[142:143]
	v_pk_mul_f32 v[88:89], v[188:189], v[88:89]
	v_pk_mul_f32 v[86:87], v[190:191], v[86:87]
	v_pk_fma_f32 v[84:85], v[84:85], v[132:133], v[144:145]
	v_cvt_pk_bf16_f32 v86, v86, v87
	v_cvt_pk_bf16_f32 v87, v88, v89
	v_mul_f32_e32 v88, v83, v83
	v_fmac_f32_e32 v88, v82, v82
	v_fmac_f32_e32 v88, v84, v84
	v_add_f32_e32 v92, v127, v92
	v_fmac_f32_e32 v88, v85, v85
	global_store_dwordx4 v[138:139], v[82:85], off offset:528
	v_add_f32_e32 v92, v92, v88
	s_nop 0
	v_pk_mul_f32 v[82:83], v[196:197], v[82:83]
	v_pk_mul_f32 v[84:85], v[194:195], v[84:85]
	v_cvt_pk_bf16_f32 v88, v82, v83
	v_mov_b32_e32 v82, v92
	s_nop 1
	v_permlane16_swap_b32_e32 v92, v82
	v_add_f32_e32 v82, v92, v82
	v_mov_b32_e32 v83, v82
	v_cvt_pk_bf16_f32 v89, v84, v85
	s_nop 0
	v_permlane32_swap_b32_e32 v82, v83
	ds_bpermute_b32 v86, v230, v86
	ds_bpermute_b32 v87, v230, v87
	ds_bpermute_b32 v88, v230, v88
	ds_bpermute_b32 v89, v230, v89
	s_waitcnt lgkmcnt(0)
	global_store_dwordx4 v[90:91], v[86:89], off offset:256
	s_and_saveexec_b64 s[16:17], vcc
	s_cbranch_execz .LBB0_919
	s_lshl_b64 s[20:21], s[14:15], 2
	s_add_u32 s20, s43, s20
	s_addc_u32 s21, s47, s21
	v_lshl_add_u64 v[84:85], v[192:193], 2, s[20:21]
	v_add_f32_e32 v82, v82, v83
	global_atomic_add_f32 v[84:85], v82, off offset:128
.LBB0_919:
	s_or_b64 exec, exec, s[16:17]
	s_waitcnt vmcnt(8)
	v_pk_fma_f32 v[78:79], v[78:79], v[114:115], v[122:123]
	v_lshl_add_u64 v[82:83], s[18:19], 0, v[128:129]
	v_mul_f32_e32 v86, v79, v79
	v_pk_fma_f32 v[80:81], v[80:81], v[116:117], v[124:125]
	v_fmac_f32_e32 v86, v78, v78
	v_lshl_add_u64 v[82:83], v[178:179], 2, v[82:83]
	v_fmac_f32_e32 v86, v80, v80
	global_store_dwordx4 v[82:83], v[78:81], off
	v_fmac_f32_e32 v86, v81, v81
	v_pk_fma_f32 v[74:75], v[74:75], v[106:107], v[110:111]
	v_pk_mul_f32 v[80:81], v[184:185], v[80:81]
	v_pk_mul_f32 v[78:79], v[186:187], v[78:79]
	v_pk_fma_f32 v[76:77], v[76:77], v[108:109], v[112:113]
	v_cvt_pk_bf16_f32 v78, v78, v79
	v_cvt_pk_bf16_f32 v79, v80, v81
	v_mul_f32_e32 v80, v75, v75
	v_fmac_f32_e32 v80, v74, v74
	v_add_u32_e32 v84, s14, v126
	v_fmac_f32_e32 v80, v76, v76
	v_ashrrev_i32_e32 v85, 31, v84
	global_store_dwordx4 v[82:83], v[74:77], off offset:16
	v_fmac_f32_e32 v80, v77, v77
	s_waitcnt vmcnt(8)
	v_pk_fma_f32 v[70:71], v[70:71], v[118:119], v[102:103]
	v_pk_mul_f32 v[76:77], v[180:181], v[76:77]
	v_lshlrev_b64 v[84:85], 11, v[84:85]
	v_pk_mul_f32 v[74:75], v[182:183], v[74:75]
	v_cvt_pk_bf16_f32 v81, v76, v77
	v_mul_f32_e32 v76, v71, v71
	v_add_f32_e32 v86, v86, v80
	v_cvt_pk_bf16_f32 v80, v74, v75
	v_lshl_add_u64 v[74:75], s[76:77], 0, v[84:85]
	v_pk_fma_f32 v[72:73], v[72:73], v[120:121], v[104:105]
	v_fmac_f32_e32 v76, v70, v70
	v_lshl_add_u64 v[74:75], v[178:179], 1, v[74:75]
	v_fmac_f32_e32 v76, v72, v72
	v_lshl_add_u64 v[74:75], v[74:75], 0, v[228:229]
	ds_bpermute_b32 v78, v230, v78
	ds_bpermute_b32 v79, v230, v79
	ds_bpermute_b32 v80, v230, v80
	ds_bpermute_b32 v81, v230, v81
	s_waitcnt lgkmcnt(0)
	global_store_dwordx4 v[74:75], v[78:81], off
	global_store_dwordx4 v[82:83], v[70:73], off offset:512
	v_fmac_f32_e32 v76, v73, v73
	v_pk_fma_f32 v[66:67], v[66:67], v[130:131], v[98:99]
	v_pk_mul_f32 v[72:73], v[188:189], v[72:73]
	v_pk_mul_f32 v[70:71], v[190:191], v[70:71]
	v_pk_fma_f32 v[68:69], v[68:69], v[132:133], v[100:101]
	v_cvt_pk_bf16_f32 v70, v70, v71
	v_cvt_pk_bf16_f32 v71, v72, v73
	v_mul_f32_e32 v72, v67, v67
	v_fmac_f32_e32 v72, v66, v66
	v_fmac_f32_e32 v72, v68, v68
	v_add_f32_e32 v76, v86, v76
	v_fmac_f32_e32 v72, v69, v69
	global_store_dwordx4 v[82:83], v[66:69], off offset:528
	v_add_f32_e32 v76, v76, v72
	s_nop 0
	v_pk_mul_f32 v[66:67], v[196:197], v[66:67]
	v_pk_mul_f32 v[68:69], v[194:195], v[68:69]
	v_cvt_pk_bf16_f32 v72, v66, v67
	v_mov_b32_e32 v66, v76
	s_nop 1
	v_permlane16_swap_b32_e32 v76, v66
	v_add_f32_e32 v66, v76, v66
	v_mov_b32_e32 v67, v66
	v_cvt_pk_bf16_f32 v73, v68, v69
	s_nop 0
	v_permlane32_swap_b32_e32 v66, v67
	ds_bpermute_b32 v70, v230, v70
	ds_bpermute_b32 v71, v230, v71
	ds_bpermute_b32 v72, v230, v72
	ds_bpermute_b32 v73, v230, v73
	s_waitcnt lgkmcnt(0)
	global_store_dwordx4 v[74:75], v[70:73], off offset:256
	s_and_saveexec_b64 s[16:17], vcc
	s_cbranch_execz .LBB0_921
; DI float xsum32(float x) { auto r = __builtin_amdgcn_permlane32_swap(__float_as_uint(x), __float_as_uint(x), false, false); return __uint_as_float(r[0]) + __uint_as_float(r[1]); }
; DI float xsum16(float x) { auto r = __builtin_amdgcn_permlane16_swap(__float_as_uint(x), __float_as_uint(x), false, false); return __uint_as_float(r[0]) + __uint_as_float(r[1]); }
; template <int EPI>
; DI void gemm_epilogue(const Params& p, int layer, f32x4 (&acc)[2][2][4][2], int brow, int bcol, int pn, int wr, int wc,
;                       int fr, int fq, char* smem, int ksplit = -1) {
;     ...
;         for (int bj = 0; bj < 2; ++bj) {
;           u32x4 ob;
; #pragma unroll
;           for (int n = 0; n < 2; ++n) {
;             const int col = colb + bj * 128 + n * 4;
;             f32x4 o = xv[mm][bj][n] + gv[bj][n] * acc[ai][bj][m][n];
;             *(f32x4*)(dst + (size_t)rl * DM + col) = o;
;             if (EPI == EPI_OUT) {
;               ssq += o[0] * o[0] + o[1] * o[1] + o[2] * o[2] + o[3] * o[3];
;               o = o * gs[bj][n];
;               ob[2 * n] = pk_bf16(o[0], o[1]);
;               ob[2 * n + 1] = pk_bf16(o[2], o[3]);
;             }
;           }
;           if (EPI == EPI_OUT) *(u32x4*)(p.xn2 + (size_t)(brow + rl) * DM + colb + bj * 128) = ob;
;         }
;         if (EPI == EPI_OUT) {
;           ssq = xsum16(ssq);
;           ssq = xsum32(ssq);
;           if (fq == 0) atomicAdd(p.rowss + (size_t)layer * NTOK + brow + rl, ssq);
	s_lshl_b64 s[20:21], s[14:15], 2
	s_add_u32 s20, s43, s20
	s_addc_u32 s21, s47, s21
	v_lshl_add_u64 v[68:69], v[192:193], 2, s[20:21]
	v_add_f32_e32 v66, v66, v67
	global_atomic_add_f32 v[68:69], v66, off offset:192
.LBB0_921:
	s_or_b64 exec, exec, s[16:17]
	v_add_u32_e32 v102, 0x80, v192
	v_add_u32_e32 v82, 0x90, v192
	v_ashrrev_i32_e32 v103, 31, v102
	v_ashrrev_i32_e32 v83, 31, v82
	v_lshlrev_b64 v[104:105], 12, v[102:103]
	v_lshlrev_b64 v[84:85], 12, v[82:83]
	v_lshl_add_u64 v[66:67], v[198:199], 0, v[104:105]
	v_lshl_add_u64 v[70:71], v[198:199], 0, v[84:85]
	global_load_dwordx4 v[86:89], v[66:67], off offset:16
	global_load_dwordx4 v[90:93], v[66:67], off
	global_load_dwordx4 v[94:97], v[66:67], off offset:528
	global_load_dwordx4 v[98:101], v[66:67], off offset:512
	global_load_dwordx4 v[74:77], v[70:71], off offset:16
	global_load_dwordx4 v[78:81], v[70:71], off
	s_nop 0
	global_load_dwordx4 v[66:69], v[70:71], off offset:528
	s_nop 0
	global_load_dwordx4 v[70:73], v[70:71], off offset:512
	s_waitcnt vmcnt(6)
	v_pk_fma_f32 v[62:63], v[62:63], v[114:115], v[90:91]
	v_lshl_add_u64 v[104:105], s[18:19], 0, v[104:105]
	v_mul_f32_e32 v83, v63, v63
	v_pk_fma_f32 v[64:65], v[64:65], v[116:117], v[92:93]
	v_fmac_f32_e32 v83, v62, v62
	v_lshl_add_u64 v[90:91], v[178:179], 2, v[104:105]
	v_fmac_f32_e32 v83, v64, v64
	global_store_dwordx4 v[90:91], v[62:65], off
	v_fmac_f32_e32 v83, v65, v65
	v_pk_fma_f32 v[58:59], v[58:59], v[106:107], v[86:87]
	v_pk_mul_f32 v[64:65], v[184:185], v[64:65]
	v_pk_mul_f32 v[62:63], v[186:187], v[62:63]
	v_pk_fma_f32 v[60:61], v[60:61], v[108:109], v[88:89]
	v_cvt_pk_bf16_f32 v62, v62, v63
	v_cvt_pk_bf16_f32 v63, v64, v65
	v_mul_f32_e32 v64, v59, v59
	v_fmac_f32_e32 v64, v58, v58
	v_add_u32_e32 v102, s14, v102
	v_fmac_f32_e32 v64, v60, v60
	v_ashrrev_i32_e32 v103, 31, v102
	global_store_dwordx4 v[90:91], v[58:61], off offset:16
	v_fmac_f32_e32 v64, v61, v61
	s_waitcnt vmcnt(6)
	v_pk_fma_f32 v[54:55], v[54:55], v[118:119], v[98:99]
	v_pk_mul_f32 v[60:61], v[180:181], v[60:61]
	v_lshlrev_b64 v[102:103], 11, v[102:103]
	v_pk_mul_f32 v[58:59], v[182:183], v[58:59]
	v_cvt_pk_bf16_f32 v65, v60, v61
	v_mul_f32_e32 v60, v55, v55
	v_add_f32_e32 v83, v83, v64
	v_cvt_pk_bf16_f32 v64, v58, v59
	v_lshl_add_u64 v[58:59], s[76:77], 0, v[102:103]
	v_pk_fma_f32 v[56:57], v[56:57], v[120:121], v[100:101]
	v_fmac_f32_e32 v60, v54, v54
	v_lshl_add_u64 v[58:59], v[178:179], 1, v[58:59]
	v_fmac_f32_e32 v60, v56, v56
	v_lshl_add_u64 v[58:59], v[58:59], 0, v[228:229]
	ds_bpermute_b32 v62, v230, v62
	ds_bpermute_b32 v63, v230, v63
	ds_bpermute_b32 v64, v230, v64
	ds_bpermute_b32 v65, v230, v65
	s_waitcnt lgkmcnt(0)
	global_store_dwordx4 v[58:59], v[62:65], off
	global_store_dwordx4 v[90:91], v[54:57], off offset:512
	v_fmac_f32_e32 v60, v57, v57
	v_pk_fma_f32 v[50:51], v[50:51], v[130:131], v[94:95]
	v_pk_mul_f32 v[56:57], v[188:189], v[56:57]
	v_pk_mul_f32 v[54:55], v[190:191], v[54:55]
	v_pk_fma_f32 v[52:53], v[52:53], v[132:133], v[96:97]
	v_cvt_pk_bf16_f32 v54, v54, v55
	v_cvt_pk_bf16_f32 v55, v56, v57
	v_mul_f32_e32 v56, v51, v51
	v_fmac_f32_e32 v56, v50, v50
	v_fmac_f32_e32 v56, v52, v52
	v_add_f32_e32 v60, v83, v60
	v_fmac_f32_e32 v56, v53, v53
	global_store_dwordx4 v[90:91], v[50:53], off offset:528
	v_add_f32_e32 v60, v60, v56
	s_nop 0
	v_pk_mul_f32 v[50:51], v[196:197], v[50:51]
	v_pk_mul_f32 v[52:53], v[194:195], v[52:53]
	v_cvt_pk_bf16_f32 v56, v50, v51
	v_mov_b32_e32 v50, v60
	s_nop 1
	v_permlane16_swap_b32_e32 v60, v50
	v_add_f32_e32 v50, v60, v50
	v_mov_b32_e32 v51, v50
	v_cvt_pk_bf16_f32 v57, v52, v53
	s_nop 0
	v_permlane32_swap_b32_e32 v50, v51
	ds_bpermute_b32 v54, v230, v54
	ds_bpermute_b32 v55, v230, v55
	ds_bpermute_b32 v56, v230, v56
	ds_bpermute_b32 v57, v230, v57
	s_waitcnt lgkmcnt(0)
	global_store_dwordx4 v[58:59], v[54:57], off offset:256
	s_and_saveexec_b64 s[16:17], vcc
	s_cbranch_execz .LBB0_923
	s_lshl_b64 s[20:21], s[14:15], 2
	s_add_u32 s20, s43, s20
	s_addc_u32 s21, s47, s21
	v_lshl_add_u64 v[52:53], v[192:193], 2, s[20:21]
	v_add_f32_e32 v50, v50, v51
	global_atomic_add_f32 v[52:53], v50, off offset:512
.LBB0_923:
	s_or_b64 exec, exec, s[16:17]
	s_waitcnt vmcnt(8)
	v_pk_fma_f32 v[46:47], v[46:47], v[114:115], v[78:79]
	v_lshl_add_u64 v[50:51], s[18:19], 0, v[84:85]
	v_mul_f32_e32 v54, v47, v47
	v_pk_fma_f32 v[48:49], v[48:49], v[116:117], v[80:81]
	v_fmac_f32_e32 v54, v46, v46
	v_lshl_add_u64 v[50:51], v[178:179], 2, v[50:51]
	v_fmac_f32_e32 v54, v48, v48
	global_store_dwordx4 v[50:51], v[46:49], off
	v_fmac_f32_e32 v54, v49, v49
	v_pk_fma_f32 v[42:43], v[42:43], v[106:107], v[74:75]
	v_pk_mul_f32 v[48:49], v[184:185], v[48:49]
	v_pk_mul_f32 v[46:47], v[186:187], v[46:47]
	v_pk_fma_f32 v[44:45], v[44:45], v[108:109], v[76:77]
	v_cvt_pk_bf16_f32 v46, v46, v47
	v_cvt_pk_bf16_f32 v47, v48, v49
	v_mul_f32_e32 v48, v43, v43
	v_fmac_f32_e32 v48, v42, v42
	v_add_u32_e32 v52, s14, v82
	v_fmac_f32_e32 v48, v44, v44
	v_ashrrev_i32_e32 v53, 31, v52
	global_store_dwordx4 v[50:51], v[42:45], off offset:16
	v_fmac_f32_e32 v48, v45, v45
	s_waitcnt vmcnt(8)
	v_pk_fma_f32 v[38:39], v[38:39], v[118:119], v[70:71]
	v_pk_mul_f32 v[44:45], v[180:181], v[44:45]
	v_lshlrev_b64 v[52:53], 11, v[52:53]
	v_pk_mul_f32 v[42:43], v[182:183], v[42:43]
	v_cvt_pk_bf16_f32 v49, v44, v45
	v_mul_f32_e32 v44, v39, v39
	v_add_f32_e32 v54, v54, v48
	v_cvt_pk_bf16_f32 v48, v42, v43
	v_lshl_add_u64 v[42:43], s[76:77], 0, v[52:53]
	v_pk_fma_f32 v[40:41], v[40:41], v[120:121], v[72:73]
	v_fmac_f32_e32 v44, v38, v38
	v_lshl_add_u64 v[42:43], v[178:179], 1, v[42:43]
	v_fmac_f32_e32 v44, v40, v40
	v_lshl_add_u64 v[42:43], v[42:43], 0, v[228:229]
	ds_bpermute_b32 v46, v230, v46
	ds_bpermute_b32 v47, v230, v47
	ds_bpermute_b32 v48, v230, v48
	ds_bpermute_b32 v49, v230, v49
	s_waitcnt lgkmcnt(0)
	global_store_dwordx4 v[42:43], v[46:49], off
	global_store_dwordx4 v[50:51], v[38:41], off offset:512
	v_fmac_f32_e32 v44, v41, v41
	v_pk_fma_f32 v[34:35], v[34:35], v[130:131], v[66:67]
	v_pk_mul_f32 v[40:41], v[188:189], v[40:41]
	v_pk_mul_f32 v[38:39], v[190:191], v[38:39]
	v_pk_fma_f32 v[36:37], v[36:37], v[132:133], v[68:69]
	v_cvt_pk_bf16_f32 v38, v38, v39
	v_cvt_pk_bf16_f32 v39, v40, v41
	v_mul_f32_e32 v40, v35, v35
	v_fmac_f32_e32 v40, v34, v34
	v_fmac_f32_e32 v40, v36, v36
	v_add_f32_e32 v44, v54, v44
	v_fmac_f32_e32 v40, v37, v37
	global_store_dwordx4 v[50:51], v[34:37], off offset:528
	v_add_f32_e32 v44, v44, v40
	s_nop 0
	v_pk_mul_f32 v[34:35], v[196:197], v[34:35]
	v_pk_mul_f32 v[36:37], v[194:195], v[36:37]
	v_cvt_pk_bf16_f32 v40, v34, v35
	v_mov_b32_e32 v34, v44
	s_nop 1
	v_permlane16_swap_b32_e32 v44, v34
	v_add_f32_e32 v34, v44, v34
	v_mov_b32_e32 v35, v34
	v_cvt_pk_bf16_f32 v41, v36, v37
	s_nop 0
	v_permlane32_swap_b32_e32 v34, v35
	ds_bpermute_b32 v38, v230, v38
	ds_bpermute_b32 v39, v230, v39
	ds_bpermute_b32 v40, v230, v40
	ds_bpermute_b32 v41, v230, v41
	s_waitcnt lgkmcnt(0)
	global_store_dwordx4 v[42:43], v[38:41], off offset:256
	s_and_saveexec_b64 s[16:17], vcc
	s_cbranch_execz .LBB0_925
; DI float xsum32(float x) { auto r = __builtin_amdgcn_permlane32_swap(__float_as_uint(x), __float_as_uint(x), false, false); return __uint_as_float(r[0]) + __uint_as_float(r[1]); }
; DI float xsum16(float x) { auto r = __builtin_amdgcn_permlane16_swap(__float_as_uint(x), __float_as_uint(x), false, false); return __uint_as_float(r[0]) + __uint_as_float(r[1]); }
; template <int EPI>
; DI void gemm_epilogue(const Params& p, int layer, f32x4 (&acc)[2][2][4][2], int brow, int bcol, int pn, int wr, int wc,
;                       int fr, int fq, char* smem, int ksplit = -1) {
;     ...
;         for (int bj = 0; bj < 2; ++bj) {
;           u32x4 ob;
; #pragma unroll
;           for (int n = 0; n < 2; ++n) {
;             const int col = colb + bj * 128 + n * 4;
;             f32x4 o = xv[mm][bj][n] + gv[bj][n] * acc[ai][bj][m][n];
;             *(f32x4*)(dst + (size_t)rl * DM + col) = o;
;             if (EPI == EPI_OUT) {
;               ssq += o[0] * o[0] + o[1] * o[1] + o[2] * o[2] + o[3] * o[3];
;               o = o * gs[bj][n];
;               ob[2 * n] = pk_bf16(o[0], o[1]);
;               ob[2 * n + 1] = pk_bf16(o[2], o[3]);
;             }
;           }
;           if (EPI == EPI_OUT) *(u32x4*)(p.xn2 + (size_t)(brow + rl) * DM + colb + bj * 128) = ob;
;         }
;         if (EPI == EPI_OUT) {
;           ssq = xsum16(ssq);
;           ssq = xsum32(ssq);
;           if (fq == 0) atomicAdd(p.rowss + (size_t)layer * NTOK + brow + rl, ssq);
	s_lshl_b64 s[20:21], s[14:15], 2
	s_add_u32 s20, s43, s20
	s_addc_u32 s21, s47, s21
	v_lshl_add_u64 v[36:37], v[192:193], 2, s[20:21]
	v_add_f32_e32 v34, v34, v35
	global_atomic_add_f32 v[36:37], v34, off offset:576
.LBB0_925:
	s_or_b64 exec, exec, s[16:17]
	v_add_u32_e32 v70, 0xa0, v192
	v_add_u32_e32 v50, 0xb0, v192
	v_ashrrev_i32_e32 v71, 31, v70
	v_ashrrev_i32_e32 v51, 31, v50
	v_lshlrev_b64 v[72:73], 12, v[70:71]
	v_lshlrev_b64 v[52:53], 12, v[50:51]
	v_lshl_add_u64 v[34:35], v[198:199], 0, v[72:73]
	v_lshl_add_u64 v[38:39], v[198:199], 0, v[52:53]
	global_load_dwordx4 v[54:57], v[34:35], off offset:16
	global_load_dwordx4 v[58:61], v[34:35], off
	global_load_dwordx4 v[62:65], v[34:35], off offset:528
	global_load_dwordx4 v[66:69], v[34:35], off offset:512
	global_load_dwordx4 v[42:45], v[38:39], off offset:16
	global_load_dwordx4 v[46:49], v[38:39], off
	s_nop 0
	global_load_dwordx4 v[34:37], v[38:39], off offset:528
	s_nop 0
	global_load_dwordx4 v[38:41], v[38:39], off offset:512
	s_waitcnt vmcnt(6)
	v_pk_fma_f32 v[30:31], v[30:31], v[114:115], v[58:59]
	v_lshl_add_u64 v[72:73], s[18:19], 0, v[72:73]
	v_mul_f32_e32 v51, v31, v31
	v_pk_fma_f32 v[32:33], v[32:33], v[116:117], v[60:61]
	v_fmac_f32_e32 v51, v30, v30
	v_lshl_add_u64 v[58:59], v[178:179], 2, v[72:73]
	v_fmac_f32_e32 v51, v32, v32
	global_store_dwordx4 v[58:59], v[30:33], off
	v_fmac_f32_e32 v51, v33, v33
	v_pk_fma_f32 v[26:27], v[26:27], v[106:107], v[54:55]
	v_pk_mul_f32 v[32:33], v[184:185], v[32:33]
	v_pk_mul_f32 v[30:31], v[186:187], v[30:31]
	v_pk_fma_f32 v[28:29], v[28:29], v[108:109], v[56:57]
	v_cvt_pk_bf16_f32 v30, v30, v31
	v_cvt_pk_bf16_f32 v31, v32, v33
	v_mul_f32_e32 v32, v27, v27
	v_fmac_f32_e32 v32, v26, v26
	v_add_u32_e32 v70, s14, v70
	v_fmac_f32_e32 v32, v28, v28
	v_ashrrev_i32_e32 v71, 31, v70
	global_store_dwordx4 v[58:59], v[26:29], off offset:16
	v_fmac_f32_e32 v32, v29, v29
	s_waitcnt vmcnt(6)
	v_pk_fma_f32 v[22:23], v[22:23], v[118:119], v[66:67]
	v_pk_mul_f32 v[28:29], v[180:181], v[28:29]
	v_lshlrev_b64 v[70:71], 11, v[70:71]
	v_pk_mul_f32 v[26:27], v[182:183], v[26:27]
	v_cvt_pk_bf16_f32 v33, v28, v29
	v_mul_f32_e32 v28, v23, v23
	v_add_f32_e32 v51, v51, v32
	v_cvt_pk_bf16_f32 v32, v26, v27
	v_lshl_add_u64 v[26:27], s[76:77], 0, v[70:71]
	v_pk_fma_f32 v[24:25], v[24:25], v[120:121], v[68:69]
	v_fmac_f32_e32 v28, v22, v22
	v_lshl_add_u64 v[26:27], v[178:179], 1, v[26:27]
	v_fmac_f32_e32 v28, v24, v24
	v_lshl_add_u64 v[26:27], v[26:27], 0, v[228:229]
	ds_bpermute_b32 v30, v230, v30
	ds_bpermute_b32 v31, v230, v31
	ds_bpermute_b32 v32, v230, v32
	ds_bpermute_b32 v33, v230, v33
	s_waitcnt lgkmcnt(0)
	global_store_dwordx4 v[26:27], v[30:33], off
	global_store_dwordx4 v[58:59], v[22:25], off offset:512
	v_fmac_f32_e32 v28, v25, v25
	v_pk_fma_f32 v[18:19], v[18:19], v[130:131], v[62:63]
	v_pk_mul_f32 v[24:25], v[188:189], v[24:25]
	v_pk_mul_f32 v[22:23], v[190:191], v[22:23]
	v_pk_fma_f32 v[20:21], v[20:21], v[132:133], v[64:65]
	v_cvt_pk_bf16_f32 v22, v22, v23
	v_cvt_pk_bf16_f32 v23, v24, v25
	v_mul_f32_e32 v24, v19, v19
	v_fmac_f32_e32 v24, v18, v18
	v_fmac_f32_e32 v24, v20, v20
	v_add_f32_e32 v28, v51, v28
	v_fmac_f32_e32 v24, v21, v21
	global_store_dwordx4 v[58:59], v[18:21], off offset:528
	v_add_f32_e32 v28, v28, v24
	s_nop 0
	v_pk_mul_f32 v[18:19], v[196:197], v[18:19]
	v_pk_mul_f32 v[20:21], v[194:195], v[20:21]
	v_cvt_pk_bf16_f32 v24, v18, v19
	v_mov_b32_e32 v18, v28
	s_nop 1
	v_permlane16_swap_b32_e32 v28, v18
	v_add_f32_e32 v18, v28, v18
	v_mov_b32_e32 v19, v18
	v_cvt_pk_bf16_f32 v25, v20, v21
	s_nop 0
	v_permlane32_swap_b32_e32 v18, v19
	ds_bpermute_b32 v22, v230, v22
	ds_bpermute_b32 v23, v230, v23
	ds_bpermute_b32 v24, v230, v24
	ds_bpermute_b32 v25, v230, v25
	s_waitcnt lgkmcnt(0)
	global_store_dwordx4 v[26:27], v[22:25], off offset:256
	s_and_saveexec_b64 s[16:17], vcc
	s_cbranch_execz .LBB0_927
	s_lshl_b64 s[20:21], s[14:15], 2
	s_add_u32 s20, s43, s20
	s_addc_u32 s21, s47, s21
	v_lshl_add_u64 v[20:21], v[192:193], 2, s[20:21]
	v_add_f32_e32 v18, v18, v19
	global_atomic_add_f32 v[20:21], v18, off offset:640
; DI float xsum32(float x) { auto r = __builtin_amdgcn_permlane32_swap(__float_as_uint(x), __float_as_uint(x), false, false); return __uint_as_float(r[0]) + __uint_as_float(r[1]); }
; DI float xsum16(float x) { auto r = __builtin_amdgcn_permlane16_swap(__float_as_uint(x), __float_as_uint(x), false, false); return __uint_as_float(r[0]) + __uint_as_float(r[1]); }
; template <int EPI>
; DI void gemm_epilogue(const Params& p, int layer, f32x4 (&acc)[2][2][4][2], int brow, int bcol, int pn, int wr, int wc,
;                       int fr, int fq, char* smem, int ksplit = -1) {
;     ...
;         for (int bj = 0; bj < 2; ++bj) {
;           u32x4 ob;
; #pragma unroll
;           for (int n = 0; n < 2; ++n) {
;             const int col = colb + bj * 128 + n * 4;
;             f32x4 o = xv[mm][bj][n] + gv[bj][n] * acc[ai][bj][m][n];
;             *(f32x4*)(dst + (size_t)rl * DM + col) = o;
;             if (EPI == EPI_OUT) {
;               ssq += o[0] * o[0] + o[1] * o[1] + o[2] * o[2] + o[3] * o[3];
;               o = o * gs[bj][n];
;               ob[2 * n] = pk_bf16(o[0], o[1]);
;               ob[2 * n + 1] = pk_bf16(o[2], o[3]);
;             }
;           }
;           if (EPI == EPI_OUT) *(u32x4*)(p.xn2 + (size_t)(brow + rl) * DM + colb + bj * 128) = ob;
;         }
;         if (EPI == EPI_OUT) {
;           ssq = xsum16(ssq);
;           ssq = xsum32(ssq);
;           if (fq == 0) atomicAdd(p.rowss + (size_t)layer * NTOK + brow + rl, ssq);
.LBB0_927:
	s_or_b64 exec, exec, s[16:17]
	s_waitcnt vmcnt(8)
	v_pk_fma_f32 v[14:15], v[14:15], v[114:115], v[46:47]
	v_lshl_add_u64 v[18:19], s[18:19], 0, v[52:53]
	v_mul_f32_e32 v22, v15, v15
	v_pk_fma_f32 v[16:17], v[16:17], v[116:117], v[48:49]
	v_fmac_f32_e32 v22, v14, v14
	v_lshl_add_u64 v[18:19], v[178:179], 2, v[18:19]
	v_fmac_f32_e32 v22, v16, v16
	global_store_dwordx4 v[18:19], v[14:17], off
	v_fmac_f32_e32 v22, v17, v17
	v_pk_fma_f32 v[10:11], v[10:11], v[106:107], v[42:43]
	v_pk_mul_f32 v[16:17], v[184:185], v[16:17]
	v_pk_mul_f32 v[14:15], v[186:187], v[14:15]
	v_pk_fma_f32 v[12:13], v[12:13], v[108:109], v[44:45]
	v_cvt_pk_bf16_f32 v14, v14, v15
	v_cvt_pk_bf16_f32 v15, v16, v17
	v_mul_f32_e32 v16, v11, v11
	v_fmac_f32_e32 v16, v10, v10
	v_add_u32_e32 v20, s14, v50
	v_fmac_f32_e32 v16, v12, v12
	v_ashrrev_i32_e32 v21, 31, v20
	global_store_dwordx4 v[18:19], v[10:13], off offset:16
	v_fmac_f32_e32 v16, v13, v13
	s_waitcnt vmcnt(8)
	v_pk_fma_f32 v[6:7], v[6:7], v[118:119], v[38:39]
	v_pk_mul_f32 v[12:13], v[180:181], v[12:13]
	v_lshlrev_b64 v[20:21], 11, v[20:21]
	v_pk_mul_f32 v[10:11], v[182:183], v[10:11]
	v_cvt_pk_bf16_f32 v17, v12, v13
	v_mul_f32_e32 v12, v7, v7
	v_add_f32_e32 v22, v22, v16
	v_cvt_pk_bf16_f32 v16, v10, v11
	v_lshl_add_u64 v[10:11], s[76:77], 0, v[20:21]
	v_pk_fma_f32 v[8:9], v[8:9], v[120:121], v[40:41]
	v_fmac_f32_e32 v12, v6, v6
	v_lshl_add_u64 v[10:11], v[178:179], 1, v[10:11]
	v_fmac_f32_e32 v12, v8, v8
	v_lshl_add_u64 v[10:11], v[10:11], 0, v[228:229]
	ds_bpermute_b32 v14, v230, v14
	ds_bpermute_b32 v15, v230, v15
	ds_bpermute_b32 v16, v230, v16
	ds_bpermute_b32 v17, v230, v17
	s_waitcnt lgkmcnt(0)
	global_store_dwordx4 v[10:11], v[14:17], off
	global_store_dwordx4 v[18:19], v[6:9], off offset:512
	v_fmac_f32_e32 v12, v9, v9
	v_pk_fma_f32 v[2:3], v[2:3], v[130:131], v[34:35]
	v_pk_mul_f32 v[8:9], v[188:189], v[8:9]
	v_pk_mul_f32 v[6:7], v[190:191], v[6:7]
	v_pk_fma_f32 v[4:5], v[4:5], v[132:133], v[36:37]
	v_cvt_pk_bf16_f32 v6, v6, v7
	v_cvt_pk_bf16_f32 v7, v8, v9
	v_mul_f32_e32 v8, v3, v3
	v_fmac_f32_e32 v8, v2, v2
	v_fmac_f32_e32 v8, v4, v4
	v_add_f32_e32 v12, v22, v12
	v_fmac_f32_e32 v8, v5, v5
	global_store_dwordx4 v[18:19], v[2:5], off offset:528
	v_add_f32_e32 v12, v12, v8
	s_nop 0
	v_pk_mul_f32 v[2:3], v[196:197], v[2:3]
	v_pk_mul_f32 v[4:5], v[194:195], v[4:5]
	v_cvt_pk_bf16_f32 v8, v2, v3
	v_mov_b32_e32 v2, v12
	s_nop 1
	v_permlane16_swap_b32_e32 v12, v2
	v_add_f32_e32 v2, v12, v2
	v_mov_b32_e32 v3, v2
	v_cvt_pk_bf16_f32 v9, v4, v5
	s_nop 0
	v_permlane32_swap_b32_e32 v2, v3
	ds_bpermute_b32 v6, v230, v6
	ds_bpermute_b32 v7, v230, v7
	ds_bpermute_b32 v8, v230, v8
	ds_bpermute_b32 v9, v230, v9
	s_waitcnt lgkmcnt(0)
	global_store_dwordx4 v[10:11], v[6:9], off offset:256
	s_and_saveexec_b64 s[16:17], vcc
	s_cbranch_execz .LBB0_929
	s_lshl_b64 s[14:15], s[14:15], 2
	s_add_u32 s14, s43, s14
	s_addc_u32 s15, s47, s15
	v_lshl_add_u64 v[4:5], v[192:193], 2, s[14:15]
	v_add_f32_e32 v2, v2, v3
	global_atomic_add_f32 v[4:5], v2, off offset:704
